# P12 conv fix-up de-serialised: 11 items per thread branch-free, loads issued 5 items ahead with counted waits (was 3 dependent rounds with per-item load waits); on top of topgen
# speedup vs baseline: 1.0017x; 1.0017x over previous
; __device__ __forceinline__ void phase_fixup(const Params& p) {
;     const int tid = threadIdx.x, G = gridDim.x; unsigned char* ws = p.ws;
;     const float* TOP = (const float*)(ws + WS_TOP); const float* BOT = (const float*)(ws + WS_BOT); bf16* ACT = (bf16*)(ws + WS_ACT);
;     const float* cw = p.in[I_CW];
;     const int gt = blockIdx.x * NTHR + tid, NGT = G * NTHR;
;     for (int i0 = gt; i0 < 128 * 2 * DFF; i0 += 4 * NGT) {
;         float Cg[4], Cv[4], bg0[4], bg1[4], bv0[4], bv1[4];
; #pragma unroll
;         for (int u = 0; u < 4; ++u) { const int i = i0 + u * NGT; Cg[u] = Cv[u] = bg0[u] = bg1[u] = bv0[u] = bv1[u] = 0.f;
;             if (i < 128 * 2 * DFF) { const int j = i % DFF, row = (i / DFF) & 1, pm = i / (2 * DFF); const int cg_ = (j >> 7) * 256 + (j & 127), cv_ = cg_ + 128;
;                 Cg[u] = TOP[((size_t)pm * 2 + row) * 11264 + cg_]; Cv[u] = TOP[((size_t)pm * 2 + row) * 11264 + cv_];
;                 if (pm % 64) { const float* b0 = BOT + ((size_t)(pm - 1) * 2) * 11264; const float* b1 = b0 + 11264; bg0[u] = b0[cg_]; bg1[u] = b1[cg_]; bv0[u] = b0[cv_]; bv1[u] = b1[cv_]; } } }
.LBB0_1785:
	s_cmp_lt_i32 s30, 13
	s_cselect_b64 s[10:11], -1, 0
	s_and_b64 s[0:1], s[10:11], s[0:1]
	s_andn2_b64 vcc, exec, s[0:1]
	s_cbranch_vccnz .LBB0_1850
	v_lshl_add_u32 v32, s96, 9, v144
	s_mov_b32 s3, 0x160000
	v_cmp_gt_i32_e32 vcc, s3, v32
	s_and_saveexec_b64 s[12:13], vcc
	s_cbranch_execz .LBB0_1849
	v_readlane_b32 s60, v244, 18
	v_readlane_b32 s61, v244, 19
	v_lshl_add_u32 v200, s96, 9, v144
	s_add_u32 s14, s28, 0x3c000000
	s_addc_u32 s15, s29, 0
	s_add_u32 s16, s28, 0x3cb00000
	s_addc_u32 s17, s29, 0
	s_add_u32 s20, s16, 0xb000
	s_addc_u32 s21, s17, 0
	s_add_u32 s18, s28, 0x18800000
	s_addc_u32 s19, s29, 0
	s_add_u32 s62, s60, 0x5800
	s_addc_u32 s63, s61, 0
	s_add_u32 s64, s60, 0xb000
	s_addc_u32 s65, s61, 0
	s_add_u32 s66, s60, 0x10800
	s_addc_u32 s67, s61, 0
	s_mov_b32 s47, 0x378e98ab
	s_mov_b32 s48, 0x3b7cd369
	s_mov_b32 s49, 0xbcc618b2
	s_mov_b32 s50, 0x3dda74e4
	s_mov_b32 s51, 0x3f228afd
	s_mov_b32 s52, 0x3e03c728
	s_mov_b32 s53, 0xbfb8aa3b
	s_mov_b32 s54, 0x42ce8ed0
	s_mov_b32 s55, 0xc2b17218
	s_brev_b32 s56, -2
	s_movk_i32 s57, 0x7fff
	v_mov_b32_e32 v201, 0x3ba10414
	v_mov_b32_e32 v202, 0xb9c68948
	v_mov_b32_e32 v203, 0x7f800000
	v_mov_b32_e32 v180, v200
	v_lshrrev_b32_e32 v181, 9, v180
	v_mul_u32_u24_e32 v14, 0x1746, v181
	v_lshrrev_b32_e32 v14, 16, v14
	v_mul_u32_u24_e32 v183, 0x1600, v14
	v_sub_u32_e32 v182, v180, v183
	v_and_b32_e32 v183, 0xffffff80, v182
	v_add_u32_e32 v184, v182, v183
	v_mul_u32_u24_e32 v183, 0x2c00, v14
	v_add_lshl_u32 v10, v183, v184, 2
	v_and_b32_e32 v185, 1, v14
	v_sub_u32_e32 v186, v14, v185
	v_add_u32_e32 v186, -2, v186
	v_max_i32_e32 v186, 0, v186
	v_mul_u32_u24_e32 v183, 0x2c00, v186
	v_add_lshl_u32 v11, v183, v184, 2
	v_lshlrev_b32_e32 v12, 2, v182
	v_lshrrev_b32_e32 v183, 1, v14
	v_lshl_or_b32 v183, v183, 8, v185
	v_mul_u32_u24_e32 v183, 0x1600, v183
	v_add_lshl_u32 v13, v183, v182, 1
	global_load_dword v0, v10, s[14:15]
	global_load_dword v1, v10, s[14:15] offset:512
	global_load_dword v2, v11, s[16:17]
	global_load_dword v4, v11, s[16:17] offset:512
	global_load_dword v3, v11, s[20:21]
	global_load_dword v5, v11, s[20:21] offset:512
	global_load_dword v6, v12, s[60:61]
	global_load_dword v8, v12, s[62:63]
	global_load_dword v7, v12, s[64:65]
	global_load_dword v9, v12, s[66:67]
	v_add_u32_e32 v180, 0x20000, v200
	v_lshrrev_b32_e32 v181, 9, v180
	v_mul_u32_u24_e32 v30, 0x1746, v181
	v_lshrrev_b32_e32 v30, 16, v30
	v_mul_u32_u24_e32 v183, 0x1600, v30
	v_sub_u32_e32 v182, v180, v183
	v_and_b32_e32 v183, 0xffffff80, v182
	v_add_u32_e32 v184, v182, v183
	v_mul_u32_u24_e32 v183, 0x2c00, v30
	v_add_lshl_u32 v26, v183, v184, 2
	v_and_b32_e32 v185, 1, v30
	v_sub_u32_e32 v186, v30, v185
	v_add_u32_e32 v186, -2, v186
	v_max_i32_e32 v186, 0, v186
	v_mul_u32_u24_e32 v183, 0x2c00, v186
	v_add_lshl_u32 v27, v183, v184, 2
	v_lshlrev_b32_e32 v28, 2, v182
	v_lshrrev_b32_e32 v183, 1, v30
	v_lshl_or_b32 v183, v183, 8, v185
	v_mul_u32_u24_e32 v183, 0x1600, v183
	v_add_lshl_u32 v29, v183, v182, 1
	global_load_dword v16, v26, s[14:15]
	global_load_dword v17, v26, s[14:15] offset:512
	global_load_dword v18, v27, s[16:17]
	global_load_dword v20, v27, s[16:17] offset:512
	global_load_dword v19, v27, s[20:21]
	global_load_dword v21, v27, s[20:21] offset:512
	global_load_dword v22, v28, s[60:61]
	global_load_dword v24, v28, s[62:63]
	global_load_dword v23, v28, s[64:65]
	global_load_dword v25, v28, s[66:67]
	v_add_u32_e32 v180, 0x40000, v200
	v_lshrrev_b32_e32 v181, 9, v180
	v_mul_u32_u24_e32 v46, 0x1746, v181
	v_lshrrev_b32_e32 v46, 16, v46
	v_mul_u32_u24_e32 v183, 0x1600, v46
	v_sub_u32_e32 v182, v180, v183
	v_and_b32_e32 v183, 0xffffff80, v182
	v_add_u32_e32 v184, v182, v183
	v_mul_u32_u24_e32 v183, 0x2c00, v46
	v_add_lshl_u32 v42, v183, v184, 2
	v_and_b32_e32 v185, 1, v46
	v_sub_u32_e32 v186, v46, v185
	v_add_u32_e32 v186, -2, v186
	v_max_i32_e32 v186, 0, v186
	v_mul_u32_u24_e32 v183, 0x2c00, v186
	v_add_lshl_u32 v43, v183, v184, 2
	v_lshlrev_b32_e32 v44, 2, v182
	v_lshrrev_b32_e32 v183, 1, v46
	v_lshl_or_b32 v183, v183, 8, v185
	v_mul_u32_u24_e32 v183, 0x1600, v183
	v_add_lshl_u32 v45, v183, v182, 1
	global_load_dword v32, v42, s[14:15]
	global_load_dword v33, v42, s[14:15] offset:512
	global_load_dword v34, v43, s[16:17]
	global_load_dword v36, v43, s[16:17] offset:512
	global_load_dword v35, v43, s[20:21]
	global_load_dword v37, v43, s[20:21] offset:512
	global_load_dword v38, v44, s[60:61]
	global_load_dword v40, v44, s[62:63]
	global_load_dword v39, v44, s[64:65]
	global_load_dword v41, v44, s[66:67]
	v_add_u32_e32 v180, 0x60000, v200
	v_lshrrev_b32_e32 v181, 9, v180
	v_mul_u32_u24_e32 v62, 0x1746, v181
	v_lshrrev_b32_e32 v62, 16, v62
	v_mul_u32_u24_e32 v183, 0x1600, v62
	v_sub_u32_e32 v182, v180, v183
	v_and_b32_e32 v183, 0xffffff80, v182
	v_add_u32_e32 v184, v182, v183
	v_mul_u32_u24_e32 v183, 0x2c00, v62
	v_add_lshl_u32 v58, v183, v184, 2
	v_and_b32_e32 v185, 1, v62
	v_sub_u32_e32 v186, v62, v185
	v_add_u32_e32 v186, -2, v186
	v_max_i32_e32 v186, 0, v186
	v_mul_u32_u24_e32 v183, 0x2c00, v186
	v_add_lshl_u32 v59, v183, v184, 2
	v_lshlrev_b32_e32 v60, 2, v182
	v_lshrrev_b32_e32 v183, 1, v62
	v_lshl_or_b32 v183, v183, 8, v185
	v_mul_u32_u24_e32 v183, 0x1600, v183
	v_add_lshl_u32 v61, v183, v182, 1
	global_load_dword v48, v58, s[14:15]
	global_load_dword v49, v58, s[14:15] offset:512
	global_load_dword v50, v59, s[16:17]
	global_load_dword v52, v59, s[16:17] offset:512
	global_load_dword v51, v59, s[20:21]
	global_load_dword v53, v59, s[20:21] offset:512
	global_load_dword v54, v60, s[60:61]
	global_load_dword v56, v60, s[62:63]
	global_load_dword v55, v60, s[64:65]
	global_load_dword v57, v60, s[66:67]
; __device__ __forceinline__ unsigned f2bf(float f) { unsigned u = __float_as_uint(f); return (u + 0x7fffu + ((u >> 16) & 1u)) >> 16; }
; __device__ __forceinline__ float gelu_f(float x) { return 0.5f * x * (1.0f + erff(x * 0.70710678118654752f)); }
; __device__ __forceinline__ void phase_fixup(const Params& p) {
;     ...
;     for (int i0 = gt; i0 < 128 * 2 * DFF; i0 += 4 * NGT) {
;         float Cg[4], Cv[4], bg0[4], bg1[4], bv0[4], bv1[4];
; #pragma unroll
;         for (int u = 0; u < 4; ++u) { const int i = i0 + u * NGT; Cg[u] = Cv[u] = bg0[u] = bg1[u] = bv0[u] = bv1[u] = 0.f;
;             if (i < 128 * 2 * DFF) { const int j = i % DFF, row = (i / DFF) & 1, pm = i / (2 * DFF); const int cg_ = (j >> 7) * 256 + (j & 127), cv_ = cg_ + 128;
;                 Cg[u] = TOP[((size_t)pm * 2 + row) * 11264 + cg_]; Cv[u] = TOP[((size_t)pm * 2 + row) * 11264 + cv_];
;                 if (pm % 64) { const float* b0 = BOT + ((size_t)(pm - 1) * 2) * 11264; const float* b1 = b0 + 11264; bg0[u] = b0[cg_]; bg1[u] = b1[cg_]; bv0[u] = b0[cv_]; bv1[u] = b1[cv_]; } } }
; #pragma unroll
;         for (int u = 0; u < 4; ++u) { const int i = i0 + u * NGT;
;             if (i < 128 * 2 * DFF) { const int j = i % DFF, row = (i / DFF) & 1, pm = i / (2 * DFF); float g = Cg[u], v = Cv[u];
;                 if (pm % 64) { if (row == 0) { g += cw[j] * bg0[u] + cw[11264 + j] * bg1[u]; v += cw[5632 + j] * bv0[u] + cw[11264 + 5632 + j] * bv1[u]; }
;                                else { g += cw[j] * bg1[u]; v += cw[5632 + j] * bv1[u]; } }
;                 ACT[(size_t)(pm * 256 + row) * DFF + j] = (bf16)f2bf(gelu_f(g) * v); } } }
	v_add_u32_e32 v180, 0x80000, v200
	v_lshrrev_b32_e32 v181, 9, v180
	v_mul_u32_u24_e32 v78, 0x1746, v181
	v_lshrrev_b32_e32 v78, 16, v78
	v_mul_u32_u24_e32 v183, 0x1600, v78
	v_sub_u32_e32 v182, v180, v183
	v_and_b32_e32 v183, 0xffffff80, v182
	v_add_u32_e32 v184, v182, v183
	v_mul_u32_u24_e32 v183, 0x2c00, v78
	v_add_lshl_u32 v74, v183, v184, 2
	v_and_b32_e32 v185, 1, v78
	v_sub_u32_e32 v186, v78, v185
	v_add_u32_e32 v186, -2, v186
	v_max_i32_e32 v186, 0, v186
	v_mul_u32_u24_e32 v183, 0x2c00, v186
	v_add_lshl_u32 v75, v183, v184, 2
	v_lshlrev_b32_e32 v76, 2, v182
	v_lshrrev_b32_e32 v183, 1, v78
	v_lshl_or_b32 v183, v183, 8, v185
	v_mul_u32_u24_e32 v183, 0x1600, v183
	v_add_lshl_u32 v77, v183, v182, 1
	global_load_dword v64, v74, s[14:15]
	global_load_dword v65, v74, s[14:15] offset:512
	global_load_dword v66, v75, s[16:17]
	global_load_dword v68, v75, s[16:17] offset:512
	global_load_dword v67, v75, s[20:21]
	global_load_dword v69, v75, s[20:21] offset:512
	global_load_dword v70, v76, s[60:61]
	global_load_dword v72, v76, s[62:63]
	global_load_dword v71, v76, s[64:65]
	global_load_dword v73, v76, s[66:67]
	v_add_u32_e32 v180, 0xa0000, v200
	v_lshrrev_b32_e32 v181, 9, v180
	v_mul_u32_u24_e32 v94, 0x1746, v181
	v_lshrrev_b32_e32 v94, 16, v94
	v_mul_u32_u24_e32 v183, 0x1600, v94
	v_sub_u32_e32 v182, v180, v183
	v_and_b32_e32 v183, 0xffffff80, v182
	v_add_u32_e32 v184, v182, v183
	v_mul_u32_u24_e32 v183, 0x2c00, v94
	v_add_lshl_u32 v90, v183, v184, 2
	v_and_b32_e32 v185, 1, v94
	v_sub_u32_e32 v186, v94, v185
	v_add_u32_e32 v186, -2, v186
	v_max_i32_e32 v186, 0, v186
	v_mul_u32_u24_e32 v183, 0x2c00, v186
	v_add_lshl_u32 v91, v183, v184, 2
	v_lshlrev_b32_e32 v92, 2, v182
	v_lshrrev_b32_e32 v183, 1, v94
	v_lshl_or_b32 v183, v183, 8, v185
	v_mul_u32_u24_e32 v183, 0x1600, v183
	v_add_lshl_u32 v93, v183, v182, 1
	s_waitcnt vmcnt(40)
	global_load_dword v80, v90, s[14:15]
	global_load_dword v81, v90, s[14:15] offset:512
	global_load_dword v82, v91, s[16:17]
	global_load_dword v84, v91, s[16:17] offset:512
	global_load_dword v83, v91, s[20:21]
	global_load_dword v85, v91, s[20:21] offset:512
	global_load_dword v86, v92, s[60:61]
	global_load_dword v88, v92, s[62:63]
	global_load_dword v87, v92, s[64:65]
	global_load_dword v89, v92, s[66:67]
	v_mul_f32_e32 v180, v7, v3
	v_mul_f32_e32 v181, v9, v5
	v_fmac_f32_e32 v180, v2, v6
	v_fmac_f32_e32 v181, v4, v8
	v_add_f32_e32 v180, v0, v180
	v_add_f32_e32 v181, v1, v181
	v_fma_f32 v182, v3, v6, v0
	v_fma_f32 v183, v5, v8, v1
	v_and_b32_e32 v184, 1, v14
	v_and_b32_e32 v185, 0x7e, v14
	v_cmp_ne_u32_e32 vcc, 0, v184
	s_nop 1
	v_cndmask_b32_e32 v180, v180, v182, vcc
	v_cndmask_b32_e32 v181, v181, v183, vcc
	v_cmp_ne_u32_e32 vcc, 0, v185
	s_nop 1
	v_cndmask_b32_e32 v186, v0, v180, vcc
	v_cndmask_b32_e32 v187, v1, v181, vcc
	v_mul_f32_e32 v188, 0x3f3504f3, v186
	v_fma_f32 v189, |v188|, s47, v202
	v_fma_f32 v189, |v188|, v189, s48
	v_fma_f32 v189, |v188|, v189, s49
	v_fma_f32 v189, |v188|, v189, s50
	v_fma_f32 v189, |v188|, v189, s51
	v_fma_f32 v189, |v188|, v189, s52
	v_fma_f32 v189, |v188|, v189, |v188|
	v_mul_f32_e32 v190, 0xbfb8aa3b, v189
	v_fma_f32 v191, v189, s53, -v190
	v_rndne_f32_e32 v192, v190
	v_fmac_f32_e32 v191, 0xb2a5705f, v189
	v_sub_f32_e32 v190, v190, v192
	v_add_f32_e32 v190, v190, v191
	v_cvt_i32_f32_e32 v193, v192
	v_exp_f32_e32 v194, v190
	v_cmp_nlt_f32_e32 vcc, s54, v189
	v_ldexp_f32 v194, v194, v193
	s_nop 0
	v_cndmask_b32_e32 v194, 0, v194, vcc
	v_cmp_ngt_f32_e32 vcc, s55, v189
	s_nop 1
	v_cndmask_b32_e32 v194, v203, v194, vcc
	v_sub_f32_e32 v194, 1.0, v194
	v_mul_f32_e32 v195, v188, v188
	v_fmamk_f32 v191, v195, 0xba1345e1, v201
	v_fmaak_f32 v191, v195, v191, 0xbcdac9b8
	v_fmaak_f32 v191, v195, v191, 0x3de703be
	v_fmaak_f32 v191, v195, v191, 0xbec09330
	v_fmaak_f32 v191, v195, v191, 0x3e0375d0
	v_fma_f32 v191, |v188|, v191, |v188|
	v_cmp_nlt_f32_e64 s[8:9], |v188|, 1.0
	s_nop 1
	v_cndmask_b32_e64 v194, v191, v194, s[8:9]
	v_bfi_b32 v194, s56, v194, v188
	v_mul_f32_e32 v186, 0.5, v186
	v_add_f32_e32 v194, 1.0, v194
	v_mul_f32_e32 v186, v186, v194
	v_mul_f32_e32 v187, v187, v186
	v_bfe_u32 v180, v187, 16, 1
	v_add3_u32 v187, v187, v180, s57
	s_nop 0
	global_store_short_d16_hi v13, v187, s[18:19]
	v_add_u32_e32 v180, 0xc0000, v200
	v_lshrrev_b32_e32 v181, 9, v180
	v_mul_u32_u24_e32 v110, 0x1746, v181
	v_lshrrev_b32_e32 v110, 16, v110
	v_mul_u32_u24_e32 v183, 0x1600, v110
	v_sub_u32_e32 v182, v180, v183
	v_and_b32_e32 v183, 0xffffff80, v182
	v_add_u32_e32 v184, v182, v183
	v_mul_u32_u24_e32 v183, 0x2c00, v110
	v_add_lshl_u32 v106, v183, v184, 2
	v_and_b32_e32 v185, 1, v110
	v_sub_u32_e32 v186, v110, v185
	v_add_u32_e32 v186, -2, v186
	v_max_i32_e32 v186, 0, v186
	v_mul_u32_u24_e32 v183, 0x2c00, v186
	v_add_lshl_u32 v107, v183, v184, 2
	v_lshlrev_b32_e32 v108, 2, v182
	v_lshrrev_b32_e32 v183, 1, v110
	v_lshl_or_b32 v183, v183, 8, v185
	v_mul_u32_u24_e32 v183, 0x1600, v183
	v_add_lshl_u32 v109, v183, v182, 1
	s_waitcnt vmcnt(41)
; __device__ __forceinline__ unsigned f2bf(float f) { unsigned u = __float_as_uint(f); return (u + 0x7fffu + ((u >> 16) & 1u)) >> 16; }
; __device__ __forceinline__ float gelu_f(float x) { return 0.5f * x * (1.0f + erff(x * 0.70710678118654752f)); }
; __device__ __forceinline__ void phase_fixup(const Params& p) {
;     ...
;     for (int i0 = gt; i0 < 128 * 2 * DFF; i0 += 4 * NGT) {
;         float Cg[4], Cv[4], bg0[4], bg1[4], bv0[4], bv1[4];
; #pragma unroll
;         for (int u = 0; u < 4; ++u) { const int i = i0 + u * NGT; Cg[u] = Cv[u] = bg0[u] = bg1[u] = bv0[u] = bv1[u] = 0.f;
;             if (i < 128 * 2 * DFF) { const int j = i % DFF, row = (i / DFF) & 1, pm = i / (2 * DFF); const int cg_ = (j >> 7) * 256 + (j & 127), cv_ = cg_ + 128;
;                 Cg[u] = TOP[((size_t)pm * 2 + row) * 11264 + cg_]; Cv[u] = TOP[((size_t)pm * 2 + row) * 11264 + cv_];
;                 if (pm % 64) { const float* b0 = BOT + ((size_t)(pm - 1) * 2) * 11264; const float* b1 = b0 + 11264; bg0[u] = b0[cg_]; bg1[u] = b1[cg_]; bv0[u] = b0[cv_]; bv1[u] = b1[cv_]; } } }
; #pragma unroll
;         for (int u = 0; u < 4; ++u) { const int i = i0 + u * NGT;
;             if (i < 128 * 2 * DFF) { const int j = i % DFF, row = (i / DFF) & 1, pm = i / (2 * DFF); float g = Cg[u], v = Cv[u];
;                 if (pm % 64) { if (row == 0) { g += cw[j] * bg0[u] + cw[11264 + j] * bg1[u]; v += cw[5632 + j] * bv0[u] + cw[11264 + 5632 + j] * bv1[u]; }
;                                else { g += cw[j] * bg1[u]; v += cw[5632 + j] * bv1[u]; } }
;                 ACT[(size_t)(pm * 256 + row) * DFF + j] = (bf16)f2bf(gelu_f(g) * v); } } }
	global_load_dword v96, v106, s[14:15]
	global_load_dword v97, v106, s[14:15] offset:512
	global_load_dword v98, v107, s[16:17]
	global_load_dword v100, v107, s[16:17] offset:512
	global_load_dword v99, v107, s[20:21]
	global_load_dword v101, v107, s[20:21] offset:512
	global_load_dword v102, v108, s[60:61]
	global_load_dword v104, v108, s[62:63]
	global_load_dword v103, v108, s[64:65]
	global_load_dword v105, v108, s[66:67]
	v_mul_f32_e32 v180, v23, v19
	v_mul_f32_e32 v181, v25, v21
	v_fmac_f32_e32 v180, v18, v22
	v_fmac_f32_e32 v181, v20, v24
	v_add_f32_e32 v180, v16, v180
	v_add_f32_e32 v181, v17, v181
	v_fma_f32 v182, v19, v22, v16
	v_fma_f32 v183, v21, v24, v17
	v_and_b32_e32 v184, 1, v30
	v_and_b32_e32 v185, 0x7e, v30
	v_cmp_ne_u32_e32 vcc, 0, v184
	s_nop 1
	v_cndmask_b32_e32 v180, v180, v182, vcc
	v_cndmask_b32_e32 v181, v181, v183, vcc
	v_cmp_ne_u32_e32 vcc, 0, v185
	s_nop 1
	v_cndmask_b32_e32 v186, v16, v180, vcc
	v_cndmask_b32_e32 v187, v17, v181, vcc
	v_mul_f32_e32 v188, 0x3f3504f3, v186
	v_fma_f32 v189, |v188|, s47, v202
	v_fma_f32 v189, |v188|, v189, s48
	v_fma_f32 v189, |v188|, v189, s49
	v_fma_f32 v189, |v188|, v189, s50
	v_fma_f32 v189, |v188|, v189, s51
	v_fma_f32 v189, |v188|, v189, s52
	v_fma_f32 v189, |v188|, v189, |v188|
	v_mul_f32_e32 v190, 0xbfb8aa3b, v189
	v_fma_f32 v191, v189, s53, -v190
	v_rndne_f32_e32 v192, v190
	v_fmac_f32_e32 v191, 0xb2a5705f, v189
	v_sub_f32_e32 v190, v190, v192
	v_add_f32_e32 v190, v190, v191
	v_cvt_i32_f32_e32 v193, v192
	v_exp_f32_e32 v194, v190
	v_cmp_nlt_f32_e32 vcc, s54, v189
	v_ldexp_f32 v194, v194, v193
	s_nop 0
	v_cndmask_b32_e32 v194, 0, v194, vcc
	v_cmp_ngt_f32_e32 vcc, s55, v189
	s_nop 1
	v_cndmask_b32_e32 v194, v203, v194, vcc
	v_sub_f32_e32 v194, 1.0, v194
	v_mul_f32_e32 v195, v188, v188
	v_fmamk_f32 v191, v195, 0xba1345e1, v201
	v_fmaak_f32 v191, v195, v191, 0xbcdac9b8
	v_fmaak_f32 v191, v195, v191, 0x3de703be
	v_fmaak_f32 v191, v195, v191, 0xbec09330
	v_fmaak_f32 v191, v195, v191, 0x3e0375d0
	v_fma_f32 v191, |v188|, v191, |v188|
	v_cmp_nlt_f32_e64 s[8:9], |v188|, 1.0
	s_nop 1
	v_cndmask_b32_e64 v194, v191, v194, s[8:9]
	v_bfi_b32 v194, s56, v194, v188
	v_mul_f32_e32 v186, 0.5, v186
	v_add_f32_e32 v194, 1.0, v194
	v_mul_f32_e32 v186, v186, v194
	v_mul_f32_e32 v187, v187, v186
	v_bfe_u32 v180, v187, 16, 1
	v_add3_u32 v187, v187, v180, s57
	s_nop 0
	global_store_short_d16_hi v29, v187, s[18:19]
	v_add_u32_e32 v180, 0xe0000, v200
	v_lshrrev_b32_e32 v181, 9, v180
	v_mul_u32_u24_e32 v126, 0x1746, v181
	v_lshrrev_b32_e32 v126, 16, v126
	v_mul_u32_u24_e32 v183, 0x1600, v126
	v_sub_u32_e32 v182, v180, v183
	v_and_b32_e32 v183, 0xffffff80, v182
	v_add_u32_e32 v184, v182, v183
	v_mul_u32_u24_e32 v183, 0x2c00, v126
	v_add_lshl_u32 v122, v183, v184, 2
	v_and_b32_e32 v185, 1, v126
	v_sub_u32_e32 v186, v126, v185
	v_add_u32_e32 v186, -2, v186
	v_max_i32_e32 v186, 0, v186
	v_mul_u32_u24_e32 v183, 0x2c00, v186
	v_add_lshl_u32 v123, v183, v184, 2
	v_lshlrev_b32_e32 v124, 2, v182
	v_lshrrev_b32_e32 v183, 1, v126
	v_lshl_or_b32 v183, v183, 8, v185
	v_mul_u32_u24_e32 v183, 0x1600, v183
	v_add_lshl_u32 v125, v183, v182, 1
	s_waitcnt vmcnt(42)
	global_load_dword v112, v122, s[14:15]
	global_load_dword v113, v122, s[14:15] offset:512
	global_load_dword v114, v123, s[16:17]
	global_load_dword v116, v123, s[16:17] offset:512
	global_load_dword v115, v123, s[20:21]
	global_load_dword v117, v123, s[20:21] offset:512
	global_load_dword v118, v124, s[60:61]
	global_load_dword v120, v124, s[62:63]
	global_load_dword v119, v124, s[64:65]
	global_load_dword v121, v124, s[66:67]
	v_mul_f32_e32 v180, v39, v35
	v_mul_f32_e32 v181, v41, v37
	v_fmac_f32_e32 v180, v34, v38
	v_fmac_f32_e32 v181, v36, v40
	v_add_f32_e32 v180, v32, v180
	v_add_f32_e32 v181, v33, v181
	v_fma_f32 v182, v35, v38, v32
	v_fma_f32 v183, v37, v40, v33
	v_and_b32_e32 v184, 1, v46
	v_and_b32_e32 v185, 0x7e, v46
	v_cmp_ne_u32_e32 vcc, 0, v184
	s_nop 1
	v_cndmask_b32_e32 v180, v180, v182, vcc
	v_cndmask_b32_e32 v181, v181, v183, vcc
	v_cmp_ne_u32_e32 vcc, 0, v185
	s_nop 1
	v_cndmask_b32_e32 v186, v32, v180, vcc
	v_cndmask_b32_e32 v187, v33, v181, vcc
	v_mul_f32_e32 v188, 0x3f3504f3, v186
	v_fma_f32 v189, |v188|, s47, v202
	v_fma_f32 v189, |v188|, v189, s48
	v_fma_f32 v189, |v188|, v189, s49
	v_fma_f32 v189, |v188|, v189, s50
	v_fma_f32 v189, |v188|, v189, s51
	v_fma_f32 v189, |v188|, v189, s52
	v_fma_f32 v189, |v188|, v189, |v188|
	v_mul_f32_e32 v190, 0xbfb8aa3b, v189
	v_fma_f32 v191, v189, s53, -v190
	v_rndne_f32_e32 v192, v190
	v_fmac_f32_e32 v191, 0xb2a5705f, v189
	v_sub_f32_e32 v190, v190, v192
	v_add_f32_e32 v190, v190, v191
	v_cvt_i32_f32_e32 v193, v192
	v_exp_f32_e32 v194, v190
	v_cmp_nlt_f32_e32 vcc, s54, v189
	v_ldexp_f32 v194, v194, v193
	s_nop 0
	v_cndmask_b32_e32 v194, 0, v194, vcc
	v_cmp_ngt_f32_e32 vcc, s55, v189
	s_nop 1
	v_cndmask_b32_e32 v194, v203, v194, vcc
	v_sub_f32_e32 v194, 1.0, v194
	v_mul_f32_e32 v195, v188, v188
	v_fmamk_f32 v191, v195, 0xba1345e1, v201
	v_fmaak_f32 v191, v195, v191, 0xbcdac9b8
	v_fmaak_f32 v191, v195, v191, 0x3de703be
	v_fmaak_f32 v191, v195, v191, 0xbec09330
	v_fmaak_f32 v191, v195, v191, 0x3e0375d0
	v_fma_f32 v191, |v188|, v191, |v188|
	v_cmp_nlt_f32_e64 s[8:9], |v188|, 1.0
	s_nop 1
	v_cndmask_b32_e64 v194, v191, v194, s[8:9]
	v_bfi_b32 v194, s56, v194, v188
	v_mul_f32_e32 v186, 0.5, v186
	v_add_f32_e32 v194, 1.0, v194
	v_mul_f32_e32 v186, v186, v194
	v_mul_f32_e32 v187, v187, v186
	v_bfe_u32 v180, v187, 16, 1
	v_add3_u32 v187, v187, v180, s57
	s_nop 0
	global_store_short_d16_hi v45, v187, s[18:19]
	v_add_u32_e32 v180, 0x100000, v200
	v_lshrrev_b32_e32 v181, 9, v180
	v_mul_u32_u24_e32 v142, 0x1746, v181
	v_lshrrev_b32_e32 v142, 16, v142
	v_mul_u32_u24_e32 v183, 0x1600, v142
	v_sub_u32_e32 v182, v180, v183
	v_and_b32_e32 v183, 0xffffff80, v182
	v_add_u32_e32 v184, v182, v183
	v_mul_u32_u24_e32 v183, 0x2c00, v142
	v_add_lshl_u32 v138, v183, v184, 2
	v_and_b32_e32 v185, 1, v142
	v_sub_u32_e32 v186, v142, v185
	v_add_u32_e32 v186, -2, v186
	v_max_i32_e32 v186, 0, v186
	v_mul_u32_u24_e32 v183, 0x2c00, v186
	v_add_lshl_u32 v139, v183, v184, 2
	v_lshlrev_b32_e32 v140, 2, v182
	v_lshrrev_b32_e32 v183, 1, v142
	v_lshl_or_b32 v183, v183, 8, v185
	v_mul_u32_u24_e32 v183, 0x1600, v183
	v_add_lshl_u32 v141, v183, v182, 1
	s_waitcnt vmcnt(43)
; __device__ __forceinline__ unsigned f2bf(float f) { unsigned u = __float_as_uint(f); return (u + 0x7fffu + ((u >> 16) & 1u)) >> 16; }
; __device__ __forceinline__ float gelu_f(float x) { return 0.5f * x * (1.0f + erff(x * 0.70710678118654752f)); }
; __device__ __forceinline__ void phase_fixup(const Params& p) {
;     ...
;     for (int i0 = gt; i0 < 128 * 2 * DFF; i0 += 4 * NGT) {
;         float Cg[4], Cv[4], bg0[4], bg1[4], bv0[4], bv1[4];
; #pragma unroll
;         for (int u = 0; u < 4; ++u) { const int i = i0 + u * NGT; Cg[u] = Cv[u] = bg0[u] = bg1[u] = bv0[u] = bv1[u] = 0.f;
;             if (i < 128 * 2 * DFF) { const int j = i % DFF, row = (i / DFF) & 1, pm = i / (2 * DFF); const int cg_ = (j >> 7) * 256 + (j & 127), cv_ = cg_ + 128;
;                 Cg[u] = TOP[((size_t)pm * 2 + row) * 11264 + cg_]; Cv[u] = TOP[((size_t)pm * 2 + row) * 11264 + cv_];
;                 if (pm % 64) { const float* b0 = BOT + ((size_t)(pm - 1) * 2) * 11264; const float* b1 = b0 + 11264; bg0[u] = b0[cg_]; bg1[u] = b1[cg_]; bv0[u] = b0[cv_]; bv1[u] = b1[cv_]; } } }
; #pragma unroll
;         for (int u = 0; u < 4; ++u) { const int i = i0 + u * NGT;
;             if (i < 128 * 2 * DFF) { const int j = i % DFF, row = (i / DFF) & 1, pm = i / (2 * DFF); float g = Cg[u], v = Cv[u];
;                 if (pm % 64) { if (row == 0) { g += cw[j] * bg0[u] + cw[11264 + j] * bg1[u]; v += cw[5632 + j] * bv0[u] + cw[11264 + 5632 + j] * bv1[u]; }
;                                else { g += cw[j] * bg1[u]; v += cw[5632 + j] * bv1[u]; } }
;                 ACT[(size_t)(pm * 256 + row) * DFF + j] = (bf16)f2bf(gelu_f(g) * v); } } }
	global_load_dword v128, v138, s[14:15]
	global_load_dword v129, v138, s[14:15] offset:512
	global_load_dword v130, v139, s[16:17]
	global_load_dword v132, v139, s[16:17] offset:512
	global_load_dword v131, v139, s[20:21]
	global_load_dword v133, v139, s[20:21] offset:512
	global_load_dword v134, v140, s[60:61]
	global_load_dword v136, v140, s[62:63]
	global_load_dword v135, v140, s[64:65]
	global_load_dword v137, v140, s[66:67]
	v_mul_f32_e32 v180, v55, v51
	v_mul_f32_e32 v181, v57, v53
	v_fmac_f32_e32 v180, v50, v54
	v_fmac_f32_e32 v181, v52, v56
	v_add_f32_e32 v180, v48, v180
	v_add_f32_e32 v181, v49, v181
	v_fma_f32 v182, v51, v54, v48
	v_fma_f32 v183, v53, v56, v49
	v_and_b32_e32 v184, 1, v62
	v_and_b32_e32 v185, 0x7e, v62
	v_cmp_ne_u32_e32 vcc, 0, v184
	s_nop 1
	v_cndmask_b32_e32 v180, v180, v182, vcc
	v_cndmask_b32_e32 v181, v181, v183, vcc
	v_cmp_ne_u32_e32 vcc, 0, v185
	s_nop 1
	v_cndmask_b32_e32 v186, v48, v180, vcc
	v_cndmask_b32_e32 v187, v49, v181, vcc
	v_mul_f32_e32 v188, 0x3f3504f3, v186
	v_fma_f32 v189, |v188|, s47, v202
	v_fma_f32 v189, |v188|, v189, s48
	v_fma_f32 v189, |v188|, v189, s49
	v_fma_f32 v189, |v188|, v189, s50
	v_fma_f32 v189, |v188|, v189, s51
	v_fma_f32 v189, |v188|, v189, s52
	v_fma_f32 v189, |v188|, v189, |v188|
	v_mul_f32_e32 v190, 0xbfb8aa3b, v189
	v_fma_f32 v191, v189, s53, -v190
	v_rndne_f32_e32 v192, v190
	v_fmac_f32_e32 v191, 0xb2a5705f, v189
	v_sub_f32_e32 v190, v190, v192
	v_add_f32_e32 v190, v190, v191
	v_cvt_i32_f32_e32 v193, v192
	v_exp_f32_e32 v194, v190
	v_cmp_nlt_f32_e32 vcc, s54, v189
	v_ldexp_f32 v194, v194, v193
	s_nop 0
	v_cndmask_b32_e32 v194, 0, v194, vcc
	v_cmp_ngt_f32_e32 vcc, s55, v189
	s_nop 1
	v_cndmask_b32_e32 v194, v203, v194, vcc
	v_sub_f32_e32 v194, 1.0, v194
	v_mul_f32_e32 v195, v188, v188
	v_fmamk_f32 v191, v195, 0xba1345e1, v201
	v_fmaak_f32 v191, v195, v191, 0xbcdac9b8
	v_fmaak_f32 v191, v195, v191, 0x3de703be
	v_fmaak_f32 v191, v195, v191, 0xbec09330
	v_fmaak_f32 v191, v195, v191, 0x3e0375d0
	v_fma_f32 v191, |v188|, v191, |v188|
	v_cmp_nlt_f32_e64 s[8:9], |v188|, 1.0
	s_nop 1
	v_cndmask_b32_e64 v194, v191, v194, s[8:9]
	v_bfi_b32 v194, s56, v194, v188
	v_mul_f32_e32 v186, 0.5, v186
	v_add_f32_e32 v194, 1.0, v194
	v_mul_f32_e32 v186, v186, v194
	v_mul_f32_e32 v187, v187, v186
	v_bfe_u32 v180, v187, 16, 1
	v_add3_u32 v187, v187, v180, s57
	s_nop 0
	global_store_short_d16_hi v61, v187, s[18:19]
	v_add_u32_e32 v180, 0x120000, v200
	v_lshrrev_b32_e32 v181, 9, v180
	v_mul_u32_u24_e32 v160, 0x1746, v181
	v_lshrrev_b32_e32 v160, 16, v160
	v_mul_u32_u24_e32 v183, 0x1600, v160
	v_sub_u32_e32 v182, v180, v183
	v_and_b32_e32 v183, 0xffffff80, v182
	v_add_u32_e32 v184, v182, v183
	v_mul_u32_u24_e32 v183, 0x2c00, v160
	v_add_lshl_u32 v156, v183, v184, 2
	v_and_b32_e32 v185, 1, v160
	v_sub_u32_e32 v186, v160, v185
	v_add_u32_e32 v186, -2, v186
	v_max_i32_e32 v186, 0, v186
	v_mul_u32_u24_e32 v183, 0x2c00, v186
	v_add_lshl_u32 v157, v183, v184, 2
	v_lshlrev_b32_e32 v158, 2, v182
	v_lshrrev_b32_e32 v183, 1, v160
	v_lshl_or_b32 v183, v183, 8, v185
	v_mul_u32_u24_e32 v183, 0x1600, v183
	v_add_lshl_u32 v159, v183, v182, 1
	s_waitcnt vmcnt(44)
	global_load_dword v146, v156, s[14:15]
	global_load_dword v147, v156, s[14:15] offset:512
	global_load_dword v148, v157, s[16:17]
	global_load_dword v150, v157, s[16:17] offset:512
	global_load_dword v149, v157, s[20:21]
	global_load_dword v151, v157, s[20:21] offset:512
	global_load_dword v152, v158, s[60:61]
	global_load_dword v154, v158, s[62:63]
	global_load_dword v153, v158, s[64:65]
	global_load_dword v155, v158, s[66:67]
	v_mul_f32_e32 v180, v71, v67
	v_mul_f32_e32 v181, v73, v69
	v_fmac_f32_e32 v180, v66, v70
	v_fmac_f32_e32 v181, v68, v72
	v_add_f32_e32 v180, v64, v180
	v_add_f32_e32 v181, v65, v181
	v_fma_f32 v182, v67, v70, v64
	v_fma_f32 v183, v69, v72, v65
	v_and_b32_e32 v184, 1, v78
	v_and_b32_e32 v185, 0x7e, v78
	v_cmp_ne_u32_e32 vcc, 0, v184
	s_nop 1
	v_cndmask_b32_e32 v180, v180, v182, vcc
	v_cndmask_b32_e32 v181, v181, v183, vcc
	v_cmp_ne_u32_e32 vcc, 0, v185
	s_nop 1
	v_cndmask_b32_e32 v186, v64, v180, vcc
	v_cndmask_b32_e32 v187, v65, v181, vcc
	v_mul_f32_e32 v188, 0x3f3504f3, v186
	v_fma_f32 v189, |v188|, s47, v202
	v_fma_f32 v189, |v188|, v189, s48
	v_fma_f32 v189, |v188|, v189, s49
	v_fma_f32 v189, |v188|, v189, s50
	v_fma_f32 v189, |v188|, v189, s51
	v_fma_f32 v189, |v188|, v189, s52
	v_fma_f32 v189, |v188|, v189, |v188|
	v_mul_f32_e32 v190, 0xbfb8aa3b, v189
	v_fma_f32 v191, v189, s53, -v190
	v_rndne_f32_e32 v192, v190
	v_fmac_f32_e32 v191, 0xb2a5705f, v189
	v_sub_f32_e32 v190, v190, v192
	v_add_f32_e32 v190, v190, v191
	v_cvt_i32_f32_e32 v193, v192
	v_exp_f32_e32 v194, v190
	v_cmp_nlt_f32_e32 vcc, s54, v189
	v_ldexp_f32 v194, v194, v193
	s_nop 0
	v_cndmask_b32_e32 v194, 0, v194, vcc
	v_cmp_ngt_f32_e32 vcc, s55, v189
	s_nop 1
	v_cndmask_b32_e32 v194, v203, v194, vcc
	v_sub_f32_e32 v194, 1.0, v194
	v_mul_f32_e32 v195, v188, v188
	v_fmamk_f32 v191, v195, 0xba1345e1, v201
	v_fmaak_f32 v191, v195, v191, 0xbcdac9b8
	v_fmaak_f32 v191, v195, v191, 0x3de703be
	v_fmaak_f32 v191, v195, v191, 0xbec09330
	v_fmaak_f32 v191, v195, v191, 0x3e0375d0
	v_fma_f32 v191, |v188|, v191, |v188|
	v_cmp_nlt_f32_e64 s[8:9], |v188|, 1.0
	s_nop 1
	v_cndmask_b32_e64 v194, v191, v194, s[8:9]
	v_bfi_b32 v194, s56, v194, v188
	v_mul_f32_e32 v186, 0.5, v186
	v_add_f32_e32 v194, 1.0, v194
	v_mul_f32_e32 v186, v186, v194
	v_mul_f32_e32 v187, v187, v186
	v_bfe_u32 v180, v187, 16, 1
	v_add3_u32 v187, v187, v180, s57
	s_nop 0
	global_store_short_d16_hi v77, v187, s[18:19]
	v_add_u32_e32 v180, 0x140000, v200
	v_lshrrev_b32_e32 v181, 9, v180
	v_mul_u32_u24_e32 v176, 0x1746, v181
	v_lshrrev_b32_e32 v176, 16, v176
	v_mul_u32_u24_e32 v183, 0x1600, v176
	v_sub_u32_e32 v182, v180, v183
	v_and_b32_e32 v183, 0xffffff80, v182
	v_add_u32_e32 v184, v182, v183
	v_mul_u32_u24_e32 v183, 0x2c00, v176
	v_add_lshl_u32 v172, v183, v184, 2
	v_and_b32_e32 v185, 1, v176
	v_sub_u32_e32 v186, v176, v185
	v_add_u32_e32 v186, -2, v186
	v_max_i32_e32 v186, 0, v186
	v_mul_u32_u24_e32 v183, 0x2c00, v186
	v_add_lshl_u32 v173, v183, v184, 2
	v_lshlrev_b32_e32 v174, 2, v182
	v_lshrrev_b32_e32 v183, 1, v176
	v_lshl_or_b32 v183, v183, 8, v185
	v_mul_u32_u24_e32 v183, 0x1600, v183
	v_add_lshl_u32 v175, v183, v182, 1
	s_waitcnt vmcnt(45)
; __device__ __forceinline__ unsigned f2bf(float f) { unsigned u = __float_as_uint(f); return (u + 0x7fffu + ((u >> 16) & 1u)) >> 16; }
; __device__ __forceinline__ float gelu_f(float x) { return 0.5f * x * (1.0f + erff(x * 0.70710678118654752f)); }
; __device__ __forceinline__ void phase_fixup(const Params& p) {
;     ...
;     for (int i0 = gt; i0 < 128 * 2 * DFF; i0 += 4 * NGT) {
;         float Cg[4], Cv[4], bg0[4], bg1[4], bv0[4], bv1[4];
; #pragma unroll
;         for (int u = 0; u < 4; ++u) { const int i = i0 + u * NGT; Cg[u] = Cv[u] = bg0[u] = bg1[u] = bv0[u] = bv1[u] = 0.f;
;             if (i < 128 * 2 * DFF) { const int j = i % DFF, row = (i / DFF) & 1, pm = i / (2 * DFF); const int cg_ = (j >> 7) * 256 + (j & 127), cv_ = cg_ + 128;
;                 Cg[u] = TOP[((size_t)pm * 2 + row) * 11264 + cg_]; Cv[u] = TOP[((size_t)pm * 2 + row) * 11264 + cv_];
;                 if (pm % 64) { const float* b0 = BOT + ((size_t)(pm - 1) * 2) * 11264; const float* b1 = b0 + 11264; bg0[u] = b0[cg_]; bg1[u] = b1[cg_]; bv0[u] = b0[cv_]; bv1[u] = b1[cv_]; } } }
; #pragma unroll
;         for (int u = 0; u < 4; ++u) { const int i = i0 + u * NGT;
;             if (i < 128 * 2 * DFF) { const int j = i % DFF, row = (i / DFF) & 1, pm = i / (2 * DFF); float g = Cg[u], v = Cv[u];
;                 if (pm % 64) { if (row == 0) { g += cw[j] * bg0[u] + cw[11264 + j] * bg1[u]; v += cw[5632 + j] * bv0[u] + cw[11264 + 5632 + j] * bv1[u]; }
;                                else { g += cw[j] * bg1[u]; v += cw[5632 + j] * bv1[u]; } }
;                 ACT[(size_t)(pm * 256 + row) * DFF + j] = (bf16)f2bf(gelu_f(g) * v); } } }
	global_load_dword v162, v172, s[14:15]
	global_load_dword v163, v172, s[14:15] offset:512
	global_load_dword v164, v173, s[16:17]
	global_load_dword v166, v173, s[16:17] offset:512
	global_load_dword v165, v173, s[20:21]
	global_load_dword v167, v173, s[20:21] offset:512
	global_load_dword v168, v174, s[60:61]
	global_load_dword v170, v174, s[62:63]
	global_load_dword v169, v174, s[64:65]
	global_load_dword v171, v174, s[66:67]
	v_mul_f32_e32 v180, v87, v83
	v_mul_f32_e32 v181, v89, v85
	v_fmac_f32_e32 v180, v82, v86
	v_fmac_f32_e32 v181, v84, v88
	v_add_f32_e32 v180, v80, v180
	v_add_f32_e32 v181, v81, v181
	v_fma_f32 v182, v83, v86, v80
	v_fma_f32 v183, v85, v88, v81
	v_and_b32_e32 v184, 1, v94
	v_and_b32_e32 v185, 0x7e, v94
	v_cmp_ne_u32_e32 vcc, 0, v184
	s_nop 1
	v_cndmask_b32_e32 v180, v180, v182, vcc
	v_cndmask_b32_e32 v181, v181, v183, vcc
	v_cmp_ne_u32_e32 vcc, 0, v185
	s_nop 1
	v_cndmask_b32_e32 v186, v80, v180, vcc
	v_cndmask_b32_e32 v187, v81, v181, vcc
	v_mul_f32_e32 v188, 0x3f3504f3, v186
	v_fma_f32 v189, |v188|, s47, v202
	v_fma_f32 v189, |v188|, v189, s48
	v_fma_f32 v189, |v188|, v189, s49
	v_fma_f32 v189, |v188|, v189, s50
	v_fma_f32 v189, |v188|, v189, s51
	v_fma_f32 v189, |v188|, v189, s52
	v_fma_f32 v189, |v188|, v189, |v188|
	v_mul_f32_e32 v190, 0xbfb8aa3b, v189
	v_fma_f32 v191, v189, s53, -v190
	v_rndne_f32_e32 v192, v190
	v_fmac_f32_e32 v191, 0xb2a5705f, v189
	v_sub_f32_e32 v190, v190, v192
	v_add_f32_e32 v190, v190, v191
	v_cvt_i32_f32_e32 v193, v192
	v_exp_f32_e32 v194, v190
	v_cmp_nlt_f32_e32 vcc, s54, v189
	v_ldexp_f32 v194, v194, v193
	s_nop 0
	v_cndmask_b32_e32 v194, 0, v194, vcc
	v_cmp_ngt_f32_e32 vcc, s55, v189
	s_nop 1
	v_cndmask_b32_e32 v194, v203, v194, vcc
	v_sub_f32_e32 v194, 1.0, v194
	v_mul_f32_e32 v195, v188, v188
	v_fmamk_f32 v191, v195, 0xba1345e1, v201
	v_fmaak_f32 v191, v195, v191, 0xbcdac9b8
	v_fmaak_f32 v191, v195, v191, 0x3de703be
	v_fmaak_f32 v191, v195, v191, 0xbec09330
	v_fmaak_f32 v191, v195, v191, 0x3e0375d0
	v_fma_f32 v191, |v188|, v191, |v188|
	v_cmp_nlt_f32_e64 s[8:9], |v188|, 1.0
	s_nop 1
	v_cndmask_b32_e64 v194, v191, v194, s[8:9]
	v_bfi_b32 v194, s56, v194, v188
	v_mul_f32_e32 v186, 0.5, v186
	v_add_f32_e32 v194, 1.0, v194
	v_mul_f32_e32 v186, v186, v194
	v_mul_f32_e32 v187, v187, v186
	v_bfe_u32 v180, v187, 16, 1
	v_add3_u32 v187, v187, v180, s57
	s_nop 0
	global_store_short_d16_hi v93, v187, s[18:19]
	s_waitcnt vmcnt(45)
	v_mul_f32_e32 v180, v103, v99
	v_mul_f32_e32 v181, v105, v101
	v_fmac_f32_e32 v180, v98, v102
	v_fmac_f32_e32 v181, v100, v104
	v_add_f32_e32 v180, v96, v180
	v_add_f32_e32 v181, v97, v181
	v_fma_f32 v182, v99, v102, v96
	v_fma_f32 v183, v101, v104, v97
	v_and_b32_e32 v184, 1, v110
	v_and_b32_e32 v185, 0x7e, v110
	v_cmp_ne_u32_e32 vcc, 0, v184
	s_nop 1
	v_cndmask_b32_e32 v180, v180, v182, vcc
	v_cndmask_b32_e32 v181, v181, v183, vcc
	v_cmp_ne_u32_e32 vcc, 0, v185
	s_nop 1
	v_cndmask_b32_e32 v186, v96, v180, vcc
	v_cndmask_b32_e32 v187, v97, v181, vcc
	v_mul_f32_e32 v188, 0x3f3504f3, v186
	v_fma_f32 v189, |v188|, s47, v202
	v_fma_f32 v189, |v188|, v189, s48
	v_fma_f32 v189, |v188|, v189, s49
	v_fma_f32 v189, |v188|, v189, s50
	v_fma_f32 v189, |v188|, v189, s51
	v_fma_f32 v189, |v188|, v189, s52
	v_fma_f32 v189, |v188|, v189, |v188|
	v_mul_f32_e32 v190, 0xbfb8aa3b, v189
	v_fma_f32 v191, v189, s53, -v190
	v_rndne_f32_e32 v192, v190
	v_fmac_f32_e32 v191, 0xb2a5705f, v189
	v_sub_f32_e32 v190, v190, v192
	v_add_f32_e32 v190, v190, v191
	v_cvt_i32_f32_e32 v193, v192
	v_exp_f32_e32 v194, v190
	v_cmp_nlt_f32_e32 vcc, s54, v189
	v_ldexp_f32 v194, v194, v193
	s_nop 0
	v_cndmask_b32_e32 v194, 0, v194, vcc
	v_cmp_ngt_f32_e32 vcc, s55, v189
	s_nop 1
	v_cndmask_b32_e32 v194, v203, v194, vcc
	v_sub_f32_e32 v194, 1.0, v194
	v_mul_f32_e32 v195, v188, v188
	v_fmamk_f32 v191, v195, 0xba1345e1, v201
	v_fmaak_f32 v191, v195, v191, 0xbcdac9b8
	v_fmaak_f32 v191, v195, v191, 0x3de703be
	v_fmaak_f32 v191, v195, v191, 0xbec09330
	v_fmaak_f32 v191, v195, v191, 0x3e0375d0
	v_fma_f32 v191, |v188|, v191, |v188|
	v_cmp_nlt_f32_e64 s[8:9], |v188|, 1.0
	s_nop 1
	v_cndmask_b32_e64 v194, v191, v194, s[8:9]
	v_bfi_b32 v194, s56, v194, v188
	v_mul_f32_e32 v186, 0.5, v186
	v_add_f32_e32 v194, 1.0, v194
	v_mul_f32_e32 v186, v186, v194
	v_mul_f32_e32 v187, v187, v186
	v_bfe_u32 v180, v187, 16, 1
	v_add3_u32 v187, v187, v180, s57
	s_nop 0
	global_store_short_d16_hi v109, v187, s[18:19]
	s_waitcnt vmcnt(35)
	v_mul_f32_e32 v180, v119, v115
	v_mul_f32_e32 v181, v121, v117
	v_fmac_f32_e32 v180, v114, v118
	v_fmac_f32_e32 v181, v116, v120
	v_add_f32_e32 v180, v112, v180
	v_add_f32_e32 v181, v113, v181
	v_fma_f32 v182, v115, v118, v112
	v_fma_f32 v183, v117, v120, v113
	v_and_b32_e32 v184, 1, v126
	v_and_b32_e32 v185, 0x7e, v126
	v_cmp_ne_u32_e32 vcc, 0, v184
	s_nop 1
	v_cndmask_b32_e32 v180, v180, v182, vcc
	v_cndmask_b32_e32 v181, v181, v183, vcc
	v_cmp_ne_u32_e32 vcc, 0, v185
	s_nop 1
	v_cndmask_b32_e32 v186, v112, v180, vcc
	v_cndmask_b32_e32 v187, v113, v181, vcc
	v_mul_f32_e32 v188, 0x3f3504f3, v186
	v_fma_f32 v189, |v188|, s47, v202
	v_fma_f32 v189, |v188|, v189, s48
	v_fma_f32 v189, |v188|, v189, s49
	v_fma_f32 v189, |v188|, v189, s50
	v_fma_f32 v189, |v188|, v189, s51
	v_fma_f32 v189, |v188|, v189, s52
	v_fma_f32 v189, |v188|, v189, |v188|
	v_mul_f32_e32 v190, 0xbfb8aa3b, v189
	v_fma_f32 v191, v189, s53, -v190
	v_rndne_f32_e32 v192, v190
	v_fmac_f32_e32 v191, 0xb2a5705f, v189
	v_sub_f32_e32 v190, v190, v192
	v_add_f32_e32 v190, v190, v191
	v_cvt_i32_f32_e32 v193, v192
	v_exp_f32_e32 v194, v190
	v_cmp_nlt_f32_e32 vcc, s54, v189
	v_ldexp_f32 v194, v194, v193
	s_nop 0
	v_cndmask_b32_e32 v194, 0, v194, vcc
	v_cmp_ngt_f32_e32 vcc, s55, v189
	s_nop 1
	v_cndmask_b32_e32 v194, v203, v194, vcc
	v_sub_f32_e32 v194, 1.0, v194
	v_mul_f32_e32 v195, v188, v188
	v_fmamk_f32 v191, v195, 0xba1345e1, v201
	v_fmaak_f32 v191, v195, v191, 0xbcdac9b8
	v_fmaak_f32 v191, v195, v191, 0x3de703be
	v_fmaak_f32 v191, v195, v191, 0xbec09330
	v_fmaak_f32 v191, v195, v191, 0x3e0375d0
	v_fma_f32 v191, |v188|, v191, |v188|
	v_cmp_nlt_f32_e64 s[8:9], |v188|, 1.0
	s_nop 1
	v_cndmask_b32_e64 v194, v191, v194, s[8:9]
	v_bfi_b32 v194, s56, v194, v188
	v_mul_f32_e32 v186, 0.5, v186
	v_add_f32_e32 v194, 1.0, v194
	v_mul_f32_e32 v186, v186, v194
	v_mul_f32_e32 v187, v187, v186
	v_bfe_u32 v180, v187, 16, 1
	v_add3_u32 v187, v187, v180, s57
	s_nop 0
	global_store_short_d16_hi v125, v187, s[18:19]
	s_waitcnt vmcnt(25)
; __device__ __forceinline__ unsigned f2bf(float f) { unsigned u = __float_as_uint(f); return (u + 0x7fffu + ((u >> 16) & 1u)) >> 16; }
; __device__ __forceinline__ float gelu_f(float x) { return 0.5f * x * (1.0f + erff(x * 0.70710678118654752f)); }
; __device__ __forceinline__ void phase_fixup(const Params& p) {
;     ...
;             if (i < 128 * 2 * DFF) { const int j = i % DFF, row = (i / DFF) & 1, pm = i / (2 * DFF); float g = Cg[u], v = Cv[u];
;                 if (pm % 64) { if (row == 0) { g += cw[j] * bg0[u] + cw[11264 + j] * bg1[u]; v += cw[5632 + j] * bv0[u] + cw[11264 + 5632 + j] * bv1[u]; }
;                                else { g += cw[j] * bg1[u]; v += cw[5632 + j] * bv1[u]; } }
;                 ACT[(size_t)(pm * 256 + row) * DFF + j] = (bf16)f2bf(gelu_f(g) * v); } } }
	v_mul_f32_e32 v180, v135, v131
	v_mul_f32_e32 v181, v137, v133
	v_fmac_f32_e32 v180, v130, v134
	v_fmac_f32_e32 v181, v132, v136
	v_add_f32_e32 v180, v128, v180
	v_add_f32_e32 v181, v129, v181
	v_fma_f32 v182, v131, v134, v128
	v_fma_f32 v183, v133, v136, v129
	v_and_b32_e32 v184, 1, v142
	v_and_b32_e32 v185, 0x7e, v142
	v_cmp_ne_u32_e32 vcc, 0, v184
	s_nop 1
	v_cndmask_b32_e32 v180, v180, v182, vcc
	v_cndmask_b32_e32 v181, v181, v183, vcc
	v_cmp_ne_u32_e32 vcc, 0, v185
	s_nop 1
	v_cndmask_b32_e32 v186, v128, v180, vcc
	v_cndmask_b32_e32 v187, v129, v181, vcc
	v_mul_f32_e32 v188, 0x3f3504f3, v186
	v_fma_f32 v189, |v188|, s47, v202
	v_fma_f32 v189, |v188|, v189, s48
	v_fma_f32 v189, |v188|, v189, s49
	v_fma_f32 v189, |v188|, v189, s50
	v_fma_f32 v189, |v188|, v189, s51
	v_fma_f32 v189, |v188|, v189, s52
	v_fma_f32 v189, |v188|, v189, |v188|
	v_mul_f32_e32 v190, 0xbfb8aa3b, v189
	v_fma_f32 v191, v189, s53, -v190
	v_rndne_f32_e32 v192, v190
	v_fmac_f32_e32 v191, 0xb2a5705f, v189
	v_sub_f32_e32 v190, v190, v192
	v_add_f32_e32 v190, v190, v191
	v_cvt_i32_f32_e32 v193, v192
	v_exp_f32_e32 v194, v190
	v_cmp_nlt_f32_e32 vcc, s54, v189
	v_ldexp_f32 v194, v194, v193
	s_nop 0
	v_cndmask_b32_e32 v194, 0, v194, vcc
	v_cmp_ngt_f32_e32 vcc, s55, v189
	s_nop 1
	v_cndmask_b32_e32 v194, v203, v194, vcc
	v_sub_f32_e32 v194, 1.0, v194
	v_mul_f32_e32 v195, v188, v188
	v_fmamk_f32 v191, v195, 0xba1345e1, v201
	v_fmaak_f32 v191, v195, v191, 0xbcdac9b8
	v_fmaak_f32 v191, v195, v191, 0x3de703be
	v_fmaak_f32 v191, v195, v191, 0xbec09330
	v_fmaak_f32 v191, v195, v191, 0x3e0375d0
	v_fma_f32 v191, |v188|, v191, |v188|
	v_cmp_nlt_f32_e64 s[8:9], |v188|, 1.0
	s_nop 1
	v_cndmask_b32_e64 v194, v191, v194, s[8:9]
	v_bfi_b32 v194, s56, v194, v188
	v_mul_f32_e32 v186, 0.5, v186
	v_add_f32_e32 v194, 1.0, v194
	v_mul_f32_e32 v186, v186, v194
	v_mul_f32_e32 v187, v187, v186
	v_bfe_u32 v180, v187, 16, 1
	v_add3_u32 v187, v187, v180, s57
	s_nop 0
	global_store_short_d16_hi v141, v187, s[18:19]
	s_waitcnt vmcnt(15)
	v_mul_f32_e32 v180, v153, v149
	v_mul_f32_e32 v181, v155, v151
	v_fmac_f32_e32 v180, v148, v152
	v_fmac_f32_e32 v181, v150, v154
	v_add_f32_e32 v180, v146, v180
	v_add_f32_e32 v181, v147, v181
	v_fma_f32 v182, v149, v152, v146
	v_fma_f32 v183, v151, v154, v147
	v_and_b32_e32 v184, 1, v160
	v_and_b32_e32 v185, 0x7e, v160
	v_cmp_ne_u32_e32 vcc, 0, v184
	s_nop 1
	v_cndmask_b32_e32 v180, v180, v182, vcc
	v_cndmask_b32_e32 v181, v181, v183, vcc
	v_cmp_ne_u32_e32 vcc, 0, v185
	s_nop 1
	v_cndmask_b32_e32 v186, v146, v180, vcc
	v_cndmask_b32_e32 v187, v147, v181, vcc
	v_mul_f32_e32 v188, 0x3f3504f3, v186
	v_fma_f32 v189, |v188|, s47, v202
	v_fma_f32 v189, |v188|, v189, s48
	v_fma_f32 v189, |v188|, v189, s49
	v_fma_f32 v189, |v188|, v189, s50
	v_fma_f32 v189, |v188|, v189, s51
	v_fma_f32 v189, |v188|, v189, s52
	v_fma_f32 v189, |v188|, v189, |v188|
	v_mul_f32_e32 v190, 0xbfb8aa3b, v189
	v_fma_f32 v191, v189, s53, -v190
	v_rndne_f32_e32 v192, v190
	v_fmac_f32_e32 v191, 0xb2a5705f, v189
	v_sub_f32_e32 v190, v190, v192
	v_add_f32_e32 v190, v190, v191
	v_cvt_i32_f32_e32 v193, v192
	v_exp_f32_e32 v194, v190
	v_cmp_nlt_f32_e32 vcc, s54, v189
	v_ldexp_f32 v194, v194, v193
	s_nop 0
	v_cndmask_b32_e32 v194, 0, v194, vcc
	v_cmp_ngt_f32_e32 vcc, s55, v189
	s_nop 1
	v_cndmask_b32_e32 v194, v203, v194, vcc
	v_sub_f32_e32 v194, 1.0, v194
	v_mul_f32_e32 v195, v188, v188
	v_fmamk_f32 v191, v195, 0xba1345e1, v201
	v_fmaak_f32 v191, v195, v191, 0xbcdac9b8
	v_fmaak_f32 v191, v195, v191, 0x3de703be
	v_fmaak_f32 v191, v195, v191, 0xbec09330
	v_fmaak_f32 v191, v195, v191, 0x3e0375d0
	v_fma_f32 v191, |v188|, v191, |v188|
	v_cmp_nlt_f32_e64 s[8:9], |v188|, 1.0
	s_nop 1
	v_cndmask_b32_e64 v194, v191, v194, s[8:9]
	v_bfi_b32 v194, s56, v194, v188
	v_mul_f32_e32 v186, 0.5, v186
	v_add_f32_e32 v194, 1.0, v194
	v_mul_f32_e32 v186, v186, v194
	v_mul_f32_e32 v187, v187, v186
	v_bfe_u32 v180, v187, 16, 1
	v_add3_u32 v187, v187, v180, s57
	s_nop 0
	global_store_short_d16_hi v159, v187, s[18:19]
	s_waitcnt vmcnt(5)
	v_mul_f32_e32 v180, v169, v165
	v_mul_f32_e32 v181, v171, v167
	v_fmac_f32_e32 v180, v164, v168
	v_fmac_f32_e32 v181, v166, v170
	v_add_f32_e32 v180, v162, v180
	v_add_f32_e32 v181, v163, v181
	v_fma_f32 v182, v165, v168, v162
	v_fma_f32 v183, v167, v170, v163
	v_and_b32_e32 v184, 1, v176
	v_and_b32_e32 v185, 0x7e, v176
	v_cmp_ne_u32_e32 vcc, 0, v184
	s_nop 1
	v_cndmask_b32_e32 v180, v180, v182, vcc
	v_cndmask_b32_e32 v181, v181, v183, vcc
	v_cmp_ne_u32_e32 vcc, 0, v185
	s_nop 1
	v_cndmask_b32_e32 v186, v162, v180, vcc
	v_cndmask_b32_e32 v187, v163, v181, vcc
	v_mul_f32_e32 v188, 0x3f3504f3, v186
	v_fma_f32 v189, |v188|, s47, v202
	v_fma_f32 v189, |v188|, v189, s48
	v_fma_f32 v189, |v188|, v189, s49
	v_fma_f32 v189, |v188|, v189, s50
	v_fma_f32 v189, |v188|, v189, s51
	v_fma_f32 v189, |v188|, v189, s52
	v_fma_f32 v189, |v188|, v189, |v188|
	v_mul_f32_e32 v190, 0xbfb8aa3b, v189
	v_fma_f32 v191, v189, s53, -v190
	v_rndne_f32_e32 v192, v190
	v_fmac_f32_e32 v191, 0xb2a5705f, v189
	v_sub_f32_e32 v190, v190, v192
	v_add_f32_e32 v190, v190, v191
	v_cvt_i32_f32_e32 v193, v192
	v_exp_f32_e32 v194, v190
	v_cmp_nlt_f32_e32 vcc, s54, v189
	v_ldexp_f32 v194, v194, v193
	s_nop 0
	v_cndmask_b32_e32 v194, 0, v194, vcc
	v_cmp_ngt_f32_e32 vcc, s55, v189
	s_nop 1
	v_cndmask_b32_e32 v194, v203, v194, vcc
	v_sub_f32_e32 v194, 1.0, v194
	v_mul_f32_e32 v195, v188, v188
	v_fmamk_f32 v191, v195, 0xba1345e1, v201
	v_fmaak_f32 v191, v195, v191, 0xbcdac9b8
	v_fmaak_f32 v191, v195, v191, 0x3de703be
	v_fmaak_f32 v191, v195, v191, 0xbec09330
	v_fmaak_f32 v191, v195, v191, 0x3e0375d0
	v_fma_f32 v191, |v188|, v191, |v188|
	v_cmp_nlt_f32_e64 s[8:9], |v188|, 1.0
	s_nop 1
	v_cndmask_b32_e64 v194, v191, v194, s[8:9]
	v_bfi_b32 v194, s56, v194, v188
	v_mul_f32_e32 v186, 0.5, v186
	v_add_f32_e32 v194, 1.0, v194
	v_mul_f32_e32 v186, v186, v194
	v_mul_f32_e32 v187, v187, v186
	v_bfe_u32 v180, v187, 16, 1
	v_add3_u32 v187, v187, v180, s57
	s_nop 0
	global_store_short_d16_hi v175, v187, s[18:19]
